# v33 with dead running-pointer math (s_mov_b64 + v_lshl_add_u64 on v[180:181]) removed from the staggered attention KV loop
# baseline (speedup 1.0000x reference)
; __device__ __forceinline__ void partialSM(f32x16& p0, f32x16& p1, float& m_reg, float& mn, float& alpha) {
;     ...
;   float mnC = -mn * C;
;   for (int r = 0; r < 16; ++r) p0[r] = fmaf(p0[r], C, mnC); for (int r = 0; r < 16; ++r) p1[r] = fmaf(p1[r], C, mnC);
;   for (int r = 0; r < 16; ++r) p0[r] = __builtin_amdgcn_exp2f(p0[r]);
; }
; __device__ __forceinline__ void finishSM(f32x16& p0, f32x16& p1, float alpha, float& l_reg, bf16x8& pa0, bf16x8& pa1, bf16x8& pa2, bf16x8& pa3) {
;   for (int r = 0; r < 16; ++r) p1[r] = __builtin_amdgcn_exp2f(p1[r]);
;   float ps = 0; for (int r = 0; r < 16; ++r) ps += p0[r]; for (int r = 0; r < 16; ++r) ps += p1[r];
;   { auto rr = __builtin_amdgcn_permlane32_swap(__float_as_uint(ps), __float_as_uint(ps), false, false);
;     ps = __uint_as_float(rr[0]) + __uint_as_float(rr[1]); }
;   l_reg = l_reg * alpha + ps;
.LBB0_86:
	v_cndmask_b32_e64 v168, v161, v205, s[0:1]
	v_mul_f32_e32 v144, 0xbe0293ee, v168
	v_mov_b32_e32 v145, v144
	v_fmamk_f32 v80, v80, 0x3e0293ee, v144
	v_fmamk_f32 v81, v81, 0x3e0293ee, v144
	v_fmamk_f32 v82, v82, 0x3e0293ee, v144
	v_fmamk_f32 v83, v83, 0x3e0293ee, v144
	v_fmamk_f32 v84, v84, 0x3e0293ee, v144
	v_fmamk_f32 v85, v85, 0x3e0293ee, v144
	v_fmamk_f32 v86, v86, 0x3e0293ee, v144
	v_fmamk_f32 v87, v87, 0x3e0293ee, v144
	v_fmamk_f32 v88, v88, 0x3e0293ee, v144
	v_fmamk_f32 v89, v89, 0x3e0293ee, v144
	v_fmamk_f32 v90, v90, 0x3e0293ee, v144
	v_fmamk_f32 v91, v91, 0x3e0293ee, v144
	v_fmamk_f32 v92, v92, 0x3e0293ee, v144
	v_fmamk_f32 v93, v93, 0x3e0293ee, v144
	v_fmamk_f32 v94, v94, 0x3e0293ee, v144
	v_fmac_f32_e32 v145, 0x3e0293ee, v95
	v_exp_f32_e32 v161, v80
	v_exp_f32_e32 v175, v81
	v_exp_f32_e32 v162, v82
	v_exp_f32_e32 v205, v83
	v_exp_f32_e32 v174, v84
	v_exp_f32_e32 v214, v85
	v_exp_f32_e32 v163, v86
	v_exp_f32_e32 v173, v87
	v_exp_f32_e32 v164, v88
	v_exp_f32_e32 v171, v89
	v_exp_f32_e32 v165, v90
	v_exp_f32_e32 v172, v91
	v_exp_f32_e32 v166, v92
	v_exp_f32_e32 v169, v93
	v_exp_f32_e32 v167, v94
	v_exp_f32_e32 v170, v145
	v_pk_fma_f32 v[158:159], v[64:65], s[22:23], v[144:145] op_sel_hi:[1,0,0]
	v_add_f32_e32 v64, v202, v203
	v_fmac_f32_e32 v64, v201, v186
	v_add_f32_e32 v186, v206, v207
	v_pk_fma_f32 v[156:157], v[66:67], s[22:23], v[144:145] op_sel_hi:[1,0,0]
	v_pk_fma_f32 v[152:153], v[68:69], s[22:23], v[144:145] op_sel_hi:[1,0,0]
	v_pk_fma_f32 v[148:149], v[70:71], s[22:23], v[144:145] op_sel_hi:[1,0,0]
	v_pk_fma_f32 v[146:147], v[72:73], s[22:23], v[144:145] op_sel_hi:[1,0,0]
	v_pk_fma_f32 v[154:155], v[74:75], s[22:23], v[144:145] op_sel_hi:[1,0,0]
	v_pk_fma_f32 v[150:151], v[76:77], s[22:23], v[144:145] op_sel_hi:[1,0,0]
	v_pk_fma_f32 v[144:145], v[78:79], s[22:23], v[144:145] op_sel_hi:[1,0,0]
	v_fmac_f32_e32 v186, v64, v204
	s_add_i32 s2, s2, 2
	s_and_b64 vcc, exec, s[42:43]
	s_waitcnt lgkmcnt(0)
	s_cbranch_vccnz .LBB0_88
	v_mov_b32_e32 v201, v160
	s_branch .LBB0_76
